# P8 barrier shadow: waves 1-7 issue fire-and-forget loads over the FFN2 gate/up bf16 weights so the next GEMM finds them in the last-level cache
# speedup vs baseline: 1.0032x; 1.0032x over previous
; __device__ __forceinline__ unsigned xb_ld(unsigned* p)              { return __hip_atomic_load(p, __ATOMIC_RELAXED, __HIP_MEMORY_SCOPE_AGENT); }
; __device__ __forceinline__ void xcd_barrier_complete(unsigned* bar, unsigned x, unsigned& nloc, unsigned& nx) {
;     const unsigned G = gridDim.x * gridDim.y * gridDim.z;
;     unsigned sum, cnt, mine, sp = 0u;
;     for (;;) {
;         sum = 0u; cnt = 0u; mine = 0u;
; #pragma unroll
;         for (unsigned j = 0; j < 16; ++j) { const unsigned c = xb_ld(&bar[XB_XCNT(j)]); sum += c; cnt += (c > 0u) ? 1u : 0u; mine = (j == x) ? c : mine; }
; __device__ __forceinline__ void xcd_barrier(const XcdBarrier& b) {
;     asm volatile("s_waitcnt vmcnt(0)" ::: "memory");
;     __syncthreads();
;     if (threadIdx.x == 0) {
;         unsigned* bar = b.bar;
;         __builtin_amdgcn_s_waitcnt(0);
;         unsigned nloc = b.st[0], nx = b.st[1];
;         if (nloc == 0u) { xcd_barrier_complete(bar, b.x, nloc, nx); b.st[0] = nloc; b.st[1] = nx; }
.LBB0_968:
	s_waitcnt vmcnt(0)
	s_waitcnt lgkmcnt(0)
	v_readlane_b32 s99, v255, 13
	s_nop 4
	s_cmp_eq_u32 s99, 0
	s_cbranch_scc1 .Ltch_skip_968
	s_mul_i32 s100, s34, 7
	s_add_i32 s100, s100, s99
	s_add_i32 s100, s100, -1
	s_mul_i32 s100, s100, 0x6800
	s_add_u32 s100, s100, 0x8a00000
	s_add_u32 s100, s92, s100
	s_addc_u32 s101, s93, 0
	v_and_b32_e32 v230, 63, v178
	v_lshlrev_b32_e32 v230, 4, v230
	global_load_dwordx4 v[226:229], v230, s[100:101] offset:0
	global_load_dwordx4 v[226:229], v230, s[100:101] offset:1024
	global_load_dwordx4 v[226:229], v230, s[100:101] offset:2048
	global_load_dwordx4 v[226:229], v230, s[100:101] offset:3072
	s_add_u32 s100, s100, 0x1000
	s_addc_u32 s101, s101, 0
	global_load_dwordx4 v[226:229], v230, s[100:101] offset:0
	global_load_dwordx4 v[226:229], v230, s[100:101] offset:1024
	global_load_dwordx4 v[226:229], v230, s[100:101] offset:2048
	global_load_dwordx4 v[226:229], v230, s[100:101] offset:3072
	s_add_u32 s100, s100, 0x1000
	s_addc_u32 s101, s101, 0
	global_load_dwordx4 v[226:229], v230, s[100:101] offset:0
	global_load_dwordx4 v[226:229], v230, s[100:101] offset:1024
	global_load_dwordx4 v[226:229], v230, s[100:101] offset:2048
	global_load_dwordx4 v[226:229], v230, s[100:101] offset:3072
	s_add_u32 s100, s100, 0x1000
	s_addc_u32 s101, s101, 0
	global_load_dwordx4 v[226:229], v230, s[100:101] offset:0
	global_load_dwordx4 v[226:229], v230, s[100:101] offset:1024
	global_load_dwordx4 v[226:229], v230, s[100:101] offset:2048
	global_load_dwordx4 v[226:229], v230, s[100:101] offset:3072
	s_add_u32 s100, s100, 0x1000
	s_addc_u32 s101, s101, 0
	global_load_dwordx4 v[226:229], v230, s[100:101] offset:0
	global_load_dwordx4 v[226:229], v230, s[100:101] offset:1024
	global_load_dwordx4 v[226:229], v230, s[100:101] offset:2048
	global_load_dwordx4 v[226:229], v230, s[100:101] offset:3072
	s_add_u32 s100, s100, 0x1000
	s_addc_u32 s101, s101, 0
	global_load_dwordx4 v[226:229], v230, s[100:101] offset:0
	global_load_dwordx4 v[226:229], v230, s[100:101] offset:1024
	global_load_dwordx4 v[226:229], v230, s[100:101] offset:2048
	global_load_dwordx4 v[226:229], v230, s[100:101] offset:3072
	s_add_u32 s100, s100, 0x1000
	s_addc_u32 s101, s101, 0
	global_load_dwordx4 v[226:229], v230, s[100:101] offset:0
	global_load_dwordx4 v[226:229], v230, s[100:101] offset:1024
.Ltch_skip_968:
	s_barrier
	s_mov_b64 s[0:1], exec
	v_readlane_b32 s2, v254, 9
	v_readlane_b32 s3, v254, 10
	s_and_b64 s[2:3], s[0:1], s[2:3]
	s_mov_b32 s62, s56
	s_mov_b64 exec, s[2:3]
	s_cbranch_execz .LBB0_1020
	s_add_i32 s2, 0, 0x26fc0
	v_mov_b32_e32 v0, s2
	s_waitcnt vmcnt(0) expcnt(0) lgkmcnt(0)
	ds_read_b32 v2, v0
	s_add_i32 s2, 0, 0x26fc4
	v_mov_b32_e32 v0, s2
	ds_read_b32 v0, v0
	s_waitcnt lgkmcnt(1)
	v_cmp_ne_u32_e32 vcc, 0, v2
	s_cbranch_vccnz .LBB0_984
	s_add_u32 s4, s92, 0x2b1a0200
	s_addc_u32 s5, s93, 0
	s_add_u32 s12, s92, 0x2b1a0400
	s_addc_u32 s13, s93, 0
	s_add_u32 s14, s92, 0x2b1a0500
	s_addc_u32 s15, s93, 0
	s_add_u32 s16, s92, 0x2b1a0600
	s_addc_u32 s17, s93, 0
	s_add_u32 s18, s92, 0x2b1a0700
	s_addc_u32 s19, s93, 0
	s_add_u32 s20, s92, 0x2b1a0800
	s_addc_u32 s21, s93, 0
	s_add_u32 s22, s92, 0x2b1a0900
	s_addc_u32 s23, s93, 0
	s_add_u32 s24, s92, 0x2b1a0a00
	s_addc_u32 s25, s93, 0
	s_add_u32 s26, s92, 0x2b1a0b00
	s_addc_u32 s27, s93, 0
	s_add_u32 s28, s92, 0x2b1a0c00
	s_addc_u32 s29, s93, 0
	s_add_u32 s36, s92, 0x2b1a0d00
	s_addc_u32 s37, s93, 0
	s_add_u32 s42, s92, 0x2b1a0e00
	s_addc_u32 s43, s93, 0
	s_add_u32 s44, s92, 0x2b1a0f00
	s_addc_u32 s45, s93, 0
	s_add_u32 s46, s92, 0x2b1a1000
	s_addc_u32 s47, s93, 0
	s_add_u32 s48, s92, 0x2b1a1100
	s_addc_u32 s49, s93, 0
	v_readlane_b32 s2, v254, 43
	s_add_u32 s52, s92, 0x2b1a1200
	v_readlane_b32 s2, v254, 8
	s_addc_u32 s53, s93, 0
	v_readlane_b32 s3, v254, 44
	s_mul_i32 s2, s95, s2
	s_add_u32 s54, s92, 0x2b1a1300
	s_mul_i32 s2, s2, s94
	s_addc_u32 s55, s93, 0
	s_mov_b32 s3, 1
	v_mov_b32_e32 v16, 0
	s_branch .LBB0_972
